# scans: RWKV consumer waves no longer raise s_setprio (GLA/producer partner wave shares the SIMD's issue slots fairly)
# baseline (speedup 1.0000x reference)
; #define SC_BAR() do { asm volatile("s_waitcnt lgkmcnt(0)" ::: "memory"); __builtin_amdgcn_s_barrier(); asm volatile("" ::: "memory"); } while (0)
; __device__ __forceinline__ int launder_v(int x) { asm volatile("" : "+v"(x)); return x; }
; __device__ __forceinline__ void phase_scans(const Params& p, unsigned char* lds) {
;     ...
;         if (wv < 4) {
;             const int rh = item & 1;
;             const int ct = launder_v(tid); const int rowl = ct >> 3, ksl = ct & 7;
;             __builtin_amdgcn_s_setprio(3);
;             float S[8];
; #pragma unroll
;             for (int j = 0; j < 8; ++j) S[j] = 0.f;
;             SC_BAR();
;             for (int ci = 0; ci < 256; ++ci) {
;                 const float* bufp = sRW + (ci & 1) * 6656;
;                 const float* sO = bufp + 4 * ksl; const float* sV = bufp + 5120 + 32 * rh + rowl;
;                 float* ydst = (ksl == 0) ? ((float*)bufp + 6144 + rowl) : (sRW + 13312 + ct);
;                 const int ystep = (ksl == 0) ? 32 : 0;
.LBB0_1522:
	s_waitcnt vmcnt(0)
	v_mov_b32_e32 v18, v171
	s_setprio 0
	s_and_b32 s6, s2, 1
	s_lshl_b32 s5, s6, 7
	v_ashrrev_i32_e32 v0, 3, v18
	v_and_b32_e32 v19, 7, v18
	s_waitcnt lgkmcnt(0)
	s_barrier
	v_cmp_eq_u32_e32 vcc, 0, v19
	v_lshlrev_b32_e32 v99, 4, v19
	v_lshl_add_u32 v101, v0, 2, s5
	v_lshlrev_b32_e32 v110, 2, v0
	v_add_u32_e32 v110, 0x6000, v110
	v_lshlrev_b32_e32 v111, 2, v18
	v_add_u32_e32 v111, 0xd000, v111
	v_cndmask_b32_e64 v112, 0, 32, vcc
	v_lshlrev_b32_e32 v112, 2, v112
	v_mov_b32_e32 v102, 0
	v_mov_b32_e32 v103, 0
	v_mov_b32_e32 v104, 0
	v_mov_b32_e32 v105, 0
	v_mov_b32_e32 v106, 0
	v_mov_b32_e32 v107, 0
	v_mov_b32_e32 v108, 0
	v_mov_b32_e32 v109, 0
	s_mov_b32 s4, 0
